# v9 stack + P7 column-tile round order reversed (pn ^ 0x3c) so the freshest columns of the 512 MB intermediate are the ones the down-projection K-loop reads first; same tiles, same math
# baseline (speedup 1.0000x reference)
; #define PG8_STAGE(bufoff, gbase, voff) do { _Pragma("unroll") for (int _i = 0; _i < 2; ++_i) \
;         __builtin_amdgcn_global_load_lds((const unsigned*)((const char*)(gbase) + (voff)[_i]), (PG8_LAS unsigned*)(lds + (bufoff) + ldsw + _i * 8192), 16, 0, 0); } while (0)
; #define PG8_BAR __builtin_amdgcn_s_barrier()
; template <class Epi, class Sched, bool ALIGN_EPI = false, bool SP2 = false>
; __device__ __forceinline__ void gemm_phase(PG8_LAS unsigned char* lds, const Gemm g, const Sched& S, const Epi& E) {
;     ...
;     const int tid = tid_, wid = __builtin_amdgcn_readfirstlane(tid >> 6), lane = tid & 63, wr = wid >> 2, wc = wid & 3, fr = lane & 15, fq = lane >> 4;
;     const int K = g.K, nt = K / BK;
;     unsigned voffA[2], voffB[2];
; #pragma unroll
;     for (int i = 0; i < 2; ++i) { int R, C; stage_rc(tid * 16 + i * 8192, R, C); const int Rb = Epi::PERM ? ((R & ~31) + perm32(R & 31)) : R;
;         voffA[i] = (unsigned)(R * K + C) * 2u; voffB[i] = (unsigned)(Rb * K + C) * 2u; }
;     ...
;     const char* cA = (const char*)g.A + (size_t)cur.pm * tstep; const char* cB = (const char*)g.Bt + (size_t)cur.pn * tstep;
;     S.a_ready(cur);
;     if constexpr (SP2) {
;         PG8_STAGE(PG8_SB(0, 0), cB, voffB); PG8_STAGE(PG8_SB(0, 1), cB + hstep, voffB); PG8_STAGE(PG8_SA(0, 0), cA, voffA); PG8_STAGE(PG8_SA(0, 1), cA + hstep, voffA);
;         if (wr == 1) PG8_BAR;
.LBB0_980:
	v_ashrrev_i32_e32 v2, 31, v10
	v_lshrrev_b32_e32 v2, 26, v2
	v_add_u32_e32 v2, v10, v2
	v_ashrrev_i32_e32 v11, 6, v2
	v_bfe_i32 v2, v10, 27, 1
	v_lshlrev_b32_e32 v1, 4, v10
	v_lshrrev_b32_e32 v2, 22, v2
	v_add_u32_e32 v2, v1, v2
	v_and_b32_e32 v2, 0xfffffc00, v2
	v_sub_u32_e32 v2, v1, v2
	v_lshrrev_b32_e32 v3, 4, v2
	v_bitop3_b32 v2, v3, v2, 32 bitop3:0x6c
	v_ashrrev_i32_e32 v4, 31, v2
	v_lshrrev_b32_e32 v4, 26, v4
	v_add_u32_e32 v4, v2, v4
	v_lshlrev_b32_e32 v3, 3, v11
	v_ashrrev_i32_e32 v12, 6, v4
	v_and_b32_e32 v4, 0xc0, v4
	v_and_b32_e32 v3, -16, v3
	v_sub_u32_e32 v2, v2, v4
	v_mov_b32_e32 v4, 1
	v_add_u32_e32 v3, v12, v3
	v_ashrrev_i16_sdwa v2, v4, sext(v2) dst_sel:DWORD dst_unused:UNUSED_PAD src0_sel:DWORD src1_sel:BYTE_0
	s_ashr_i32 s0, s7, 3
	v_lshlrev_b32_e32 v5, 5, v11
	v_bfe_i32 v13, v2, 0, 16
	v_lshlrev_b32_e32 v2, 1, v3
	v_lshrrev_b32_e32 v6, 2, v3
	v_and_b32_e32 v7, 3, v12
	s_mov_b32 s7, 0x7ffe0
	v_and_b32_e32 v5, 32, v5
	v_and_b32_e32 v2, 24, v2
	v_and_b32_e32 v6, 4, v6
	v_and_or_b32 v7, v3, s7, v7
	v_or3_b32 v2, v7, v6, v2
	v_add_lshl_u32 v5, v5, v13, 1
	v_add_u32_e32 v1, 0x2000, v1
	v_lshl_add_u32 v132, v2, 13, v5
	v_ashrrev_i32_e32 v2, 31, v1
	v_lshrrev_b32_e32 v2, 22, v2
	v_add_u32_e32 v2, v1, v2
	v_ashrrev_i32_e32 v14, 10, v2
	v_mul_i32_i24_e32 v2, 0x400, v14
	v_sub_u32_e32 v1, v1, v2
	v_lshrrev_b32_e32 v2, 4, v1
	v_bitop3_b32 v1, v2, v1, 32 bitop3:0x6c
	v_lshl_add_u32 v130, v3, 13, v5
	v_ashrrev_i32_e32 v3, 31, v1
	v_lshrrev_b32_e32 v3, 26, v3
	v_add_u32_e32 v3, v1, v3
	s_add_i32 s0, s6, s0
	v_lshlrev_b32_e32 v2, 3, v14
	v_ashrrev_i32_e32 v15, 6, v3
	v_and_b32_e32 v3, 0xc0, v3
	s_ashr_i32 s6, s0, 31
	v_and_b32_e32 v2, -16, v2
	v_sub_u32_e32 v1, v1, v3
	s_lshr_b32 s6, s6, 23
	v_add_u32_e32 v2, v15, v2
	v_ashrrev_i16_sdwa v1, v4, sext(v1) dst_sel:DWORD dst_unused:UNUSED_PAD src0_sel:DWORD src1_sel:BYTE_0
	v_and_b32_e32 v4, 3, v15
	s_add_i32 s6, s0, s6
	v_and_or_b32 v4, v2, s7, v4
	s_ashr_i32 s7, s6, 9
	s_and_b32 s6, s6, 0xfffffe00
	s_sub_i32 s6, s0, s6
	s_sext_i32_i16 s0, s6
	s_bfe_u32 s0, s0, 0x3001c
	s_add_i32 s13, s6, s0
	s_sext_i32_i16 s0, s13
	s_and_b32 s13, s13, 0xfff8
	s_sub_i32 s6, s6, s13
	s_lshl_b32 s7, s7, 3
	s_sext_i32_i16 s6, s6
	s_ashr_i32 s1, s14, 8
	s_lshr_b32 s0, s0, 3
	s_xor_b32 s0, s0, 0x3c
	s_add_i32 s38, s7, s6
	s_ashr_i32 s12, s14, 6
	s_ashr_i32 s39, s38, 31
	s_bfe_i64 s[20:21], s[0:1], 0x100000
	s_lshl_b32 s33, s12, 10
	s_lshl_b64 s[6:7], s[38:39], 21
	s_lshl_b64 s[20:21], s[20:21], 21
	s_add_u32 s42, s76, s20
	v_lshlrev_b32_e32 v5, 5, v14
	v_bfe_i32 v16, v1, 0, 16
	v_lshlrev_b32_e32 v1, 1, v2
	v_lshrrev_b32_e32 v3, 2, v2
	s_addc_u32 s43, s77, s21
	s_add_i32 s39, s33, 0
	v_and_b32_e32 v5, 32, v5
	v_and_b32_e32 v1, 24, v1
	v_and_b32_e32 v3, 4, v3
	s_add_i32 m0, s39, 0x10000
	v_or3_b32 v1, v4, v3, v1
	v_add_lshl_u32 v3, v5, v16, 1
	global_load_lds_dwordx4 v132, s[42:43]
	s_add_i32 m0, s39, 0x12000
	v_lshl_add_u32 v136, v1, 13, v3
	s_add_u32 s20, s42, 0x100000
	global_load_lds_dwordx4 v136, s[42:43]
	s_addc_u32 s21, s43, 0
	s_add_i32 m0, s39, 0x14000
	v_lshl_add_u32 v134, v2, 13, v3
	global_load_lds_dwordx4 v132, s[20:21]
	s_add_i32 m0, s39, 0x16000
	s_add_u32 s40, s74, s6
	v_readlane_b32 s6, v247, 29
	s_addc_u32 s41, s6, s7
	s_add_i32 s46, s39, 0x2000
	global_load_lds_dwordx4 v136, s[20:21]
	s_mov_b32 m0, s39
	s_add_u32 s6, s40, 0x100000
	global_load_lds_dwordx4 v130, s[40:41]
	s_mov_b32 m0, s46
	s_addc_u32 s7, s41, 0
	s_add_i32 s47, s39, 0x4000
	global_load_lds_dwordx4 v134, s[40:41]
	s_mov_b32 m0, s47
	s_add_i32 s48, s39, 0x6000
	global_load_lds_dwordx4 v130, s[6:7]
	s_mov_b32 m0, s48
	v_mov_b32_e32 v133, 0
	global_load_lds_dwordx4 v134, s[6:7]
	v_mov_b32_e32 v137, v133
	v_mov_b32_e32 v131, v133
	v_mov_b32_e32 v135, v133
	s_cmp_eq_u32 s1, 1
	s_mov_b32 s49, 0
	v_lshl_add_u64 v[8:9], s[42:43], 0, v[132:133]
	v_lshl_add_u64 v[6:7], s[42:43], 0, v[136:137]
	v_lshl_add_u64 v[2:3], s[40:41], 0, v[130:131]
	s_cselect_b64 s[6:7], -1, 0
	s_cmp_lg_u32 s1, 1
	v_lshl_add_u64 v[4:5], s[40:41], 0, v[134:135]
	s_cbranch_scc1 .LBB0_982
	s_barrier

;     __host__ __device__ bool next(int i, Unit& u) const {
;     ...
;         int wgid = (int)L; { const int q = nwg / NXCD, r = nwg % NXCD, xcd = wgid % NXCD, off = wgid / NXCD; wgid = (xcd < r ? xcd * (q + 1) : r * (q + 1) + (xcd - r) * q) + off; }
;         const int nig = WGM * nN, gid = wgid / nig, fm = gid * WGM, gsz = (nM - fm) < WGM ? (nM - fm) : WGM;
;         u.pm = fm + ((wgid % nig) % gsz); u.pn = (wgid % nig) / gsz; return true;
.LBB0_990:
	s_ashr_i32 s28, s30, 3
	s_add_i32 s28, s34, s28
	s_ashr_i32 s29, s28, 31
	s_lshr_b32 s29, s29, 23
	s_add_i32 s29, s28, s29
	s_ashr_i32 s30, s29, 9
	s_lshl_b32 s30, s30, 3
	s_sub_i32 s31, 64, s30
	s_min_i32 s31, s31, 8
	s_abs_i32 s34, s31
	v_cvt_f32_u32_e32 v2, s34
	s_sub_i32 s36, 0, s34
	s_and_b32 s29, s29, 0xfffffe00
	s_sub_i32 s29, s28, s29
	v_rcp_iflag_f32_e32 v2, v2
	s_abs_i32 s28, s29
	s_xor_b32 s35, s29, s31
	s_ashr_i32 s35, s35, 31
	v_mul_f32_e32 v2, 0x4f7ffffe, v2
	v_cvt_u32_f32_e32 v2, v2
	s_nop 0
	v_readfirstlane_b32 s37, v2
	s_mul_i32 s36, s36, s37
	s_mul_hi_u32 s36, s37, s36
	s_add_i32 s37, s37, s36
	s_mul_hi_u32 s36, s28, s37
	s_mul_i32 s37, s36, s34
	s_sub_i32 s28, s28, s37
	s_add_i32 s44, s36, 1
	s_sub_i32 s37, s28, s34
	s_cmp_ge_u32 s28, s34
	s_cselect_b32 s36, s44, s36
	s_cselect_b32 s28, s37, s28
	s_add_i32 s37, s36, 1
	s_cmp_ge_u32 s28, s34
	s_cselect_b32 s28, s37, s36
	s_xor_b32 s28, s28, s35
	s_sub_i32 s28, s28, s35
	s_mul_i32 s31, s28, s31
	s_sub_i32 s29, s29, s31
	s_add_i32 s30, s30, s29
	s_xor_b32 s28, s28, 0x3c
